# conv_gu: the two column-scale loads of an item are issued ahead of its data loads; no wait on the first store before the second half
# baseline (speedup 1.0000x reference)
.LBB0_65:
	s_mul_hi_i32 s46, s45, 0x2fa0be83
	s_lshr_b32 s47, s46, 31
	s_ashr_i32 s46, s46, 6
	s_add_i32 s84, s46, s47
	s_mul_i32 s46, s84, 0xffffd500
	s_mul_i32 s47, s84, 0xffffaa00
	s_add_i32 s46, s43, s46
	s_add_i32 s47, s44, s47
	s_and_b32 s48, s46, 0x60
	s_and_b32 s47, s47, 0xffffff00
	s_or_b32 s48, s48, s40
	s_mul_i32 s80, s84, 0x2b0000
	s_or_b32 s48, s48, s47
	s_mul_hi_i32 s49, s84, 0x2b0000
	s_add_u32 s80, s42, s80
	s_addc_u32 s49, s41, s49
	s_ashr_i32 s47, s46, 31
	s_lshl_b64 s[46:47], s[46:47], 2
	s_add_u32 s46, s80, s46
	s_addc_u32 s47, s49, s47
	v_mov_b32_e32 v13, v143
	v_mov_b32_e32 v15, v143
	v_mov_b32_e32 v17, v143
	v_mov_b32_e32 v19, v143
	v_mov_b32_e32 v21, v143
	v_lshl_add_u64 v[2:3], s[46:47], 0, v[142:143]
	v_lshl_add_u64 v[48:49], v[2:3], 0, v[12:13]
	v_lshl_add_u64 v[26:27], v[2:3], 0, v[14:15]
	v_lshl_add_u64 v[36:37], v[2:3], 0, v[16:17]
	v_lshl_add_u64 v[40:41], v[2:3], 0, v[18:19]
	v_lshl_add_u64 v[2:3], v[2:3], 0, v[20:21]
	s_mov_b32 s10, s48
	s_ashr_i32 s11, s48, 31
	v_lshl_add_u64 v[198:199], s[10:11], 2, v[10:11]
	global_load_dword v200, v[198:199], off
	global_load_dword v201, v[198:199], off offset:64
	global_load_dwordx4 v[22:25], v[48:49], off nt
	s_nop 0
	global_load_dwordx4 v[26:29], v[26:27], off nt
	s_nop 0
	global_load_dwordx4 v[36:39], v[36:37], off nt
	s_nop 0
	global_load_dwordx4 v[40:43], v[40:41], off nt
	s_nop 0
	global_load_dwordx4 v[44:47], v[2:3], off nt
	v_add_co_u32_e32 v2, vcc, s53, v48
	v_add_u32_e32 v35, v30, v31
	s_nop 0
	v_addc_co_u32_e32 v3, vcc, 0, v49, vcc
	v_add_co_u32_e32 v52, vcc, s79, v48
	v_add_u32_e32 v62, 0x420, v35
	s_nop 0
	v_addc_co_u32_e32 v53, vcc, 0, v49, vcc
	v_add_co_u32_e32 v56, vcc, s33, v48
	v_add_u32_e32 v63, 0x428, v35
	s_nop 0
	v_addc_co_u32_e32 v57, vcc, 0, v49, vcc
	global_load_dwordx4 v[48:51], v[2:3], off nt
	s_nop 0
	global_load_dwordx4 v[52:55], v[52:53], off nt
	s_nop 0
	global_load_dwordx4 v[56:59], v[56:57], off nt
	v_add_u32_e32 v65, 0x840, v35
	v_add_u32_e32 v66, 0x848, v35
	v_add_u32_e32 v67, 0xc60, v35
	v_add_u32_e32 v68, 0xc68, v35
	v_add_u32_e32 v69, 0x1080, v35
	v_add_u32_e32 v70, 0x1088, v35
	v_add_u32_e32 v71, 0x14a0, v35
	v_add_u32_e32 v72, 0x14a8, v35
	v_add_u32_e32 v73, 0x18c0, v35
	v_add_u32_e32 v74, 0x18c8, v35
	v_add_u32_e32 v75, 0x1ce0, v35
	v_add_u32_e32 v76, 0x1ce8, v35
	s_ashr_i32 s49, s48, 31
	v_lshl_add_u64 v[4:5], s[48:49], 2, v[10:11]
	s_lshl_b64 s[80:81], s[48:49], 12
	s_add_u32 s46, s51, s80
	s_addc_u32 s47, s52, s81
	s_lshl_b32 s48, s84, 6
	s_ashr_i32 s49, s48, 31
	s_add_u32 s46, s46, s48
	s_addc_u32 s47, s47, s49
	v_lshl_add_u64 v[2:3], s[46:47], 0, v[144:145]
	v_add_u32_e32 v64, 0x400, v149
	v_lshl_add_u64 v[60:61], v[2:3], 0, v[6:7]
	s_add_i32 s45, s45, s8
	s_add_i32 s43, s43, s37
	s_add_i32 s44, s44, s55
	s_cmpk_lt_i32 s45, 0x5600
	s_waitcnt vmcnt(7)
	ds_write2_b32 v35, v22, v23 offset1:1
	ds_write2_b32 v35, v24, v25 offset0:2 offset1:3
	s_waitcnt vmcnt(6)
	ds_write2_b32 v69, v26, v27 offset1:1
	ds_write2_b32 v70, v28, v29 offset1:1
	s_waitcnt vmcnt(5)
	ds_write2_b32 v71, v36, v37 offset1:1
	ds_write2_b32 v72, v38, v39 offset1:1
	s_waitcnt vmcnt(4)
	ds_write2_b32 v73, v40, v41 offset1:1
	ds_write2_b32 v74, v42, v43 offset1:1
	s_waitcnt vmcnt(3)
	ds_write2_b32 v75, v44, v45 offset1:1
	ds_write2_b32 v76, v46, v47 offset1:1
	s_waitcnt vmcnt(2)
	ds_write2_b32 v62, v48, v49 offset1:1
	ds_write2_b32 v63, v50, v51 offset1:1
	s_waitcnt vmcnt(1)
	ds_write2_b32 v65, v52, v53 offset1:1
	ds_write2_b32 v66, v54, v55 offset1:1
	s_waitcnt vmcnt(0)
	ds_write2_b32 v67, v56, v57 offset1:1
	ds_write2_b32 v68, v58, v59 offset1:1
	s_waitcnt lgkmcnt(0)
	v_mov_b32_e32 v13, v200
	ds_read2_b32 v[26:27], v149 offset1:16
	ds_read2_b32 v[28:29], v149 offset0:33 offset1:49
	ds_read2_b32 v[36:37], v149 offset0:66 offset1:82
	ds_read2_b32 v[38:39], v149 offset0:99 offset1:115
	ds_read2_b32 v[40:41], v149 offset0:132 offset1:148
	ds_read2_b32 v[42:43], v149 offset0:165 offset1:181
	ds_read2_b32 v[44:45], v149 offset0:198 offset1:214
	ds_read2_b32 v[46:47], v149 offset0:231 offset1:247
	ds_read2_b32 v[48:49], v64 offset0:8 offset1:24
	ds_read2_b32 v[50:51], v64 offset0:41 offset1:57
	ds_read2_b32 v[52:53], v64 offset0:74 offset1:90
	ds_read2_b32 v[54:55], v64 offset0:107 offset1:123
	ds_read2_b32 v[56:57], v64 offset0:140 offset1:156
	ds_read2_b32 v[58:59], v64 offset0:173 offset1:189
	ds_read2_b32 v[62:63], v64 offset0:206 offset1:222
	ds_read2_b32 v[64:65], v64 offset0:239 offset1:255
	s_waitcnt lgkmcnt(14)
	v_mov_b32_e32 v22, v26
	v_mov_b32_e32 v24, v28
	s_waitcnt lgkmcnt(10)
	v_mov_b32_e32 v25, v42
	v_mov_b32_e32 v68, v38
	s_waitcnt lgkmcnt(8)
	v_mov_b32_e32 v69, v46
	s_waitcnt lgkmcnt(6)
	v_mov_b32_e32 v72, v50
	s_waitcnt lgkmcnt(2)
	v_mov_b32_e32 v73, v58
	v_mov_b32_e32 v74, v52
	s_waitcnt lgkmcnt(1)
	v_mov_b32_e32 v75, v62
	v_mov_b32_e32 v76, v54
	s_waitcnt lgkmcnt(0)
	v_mov_b32_e32 v77, v64
	v_mov_b32_e32 v23, v40
	v_mov_b32_e32 v66, v36
	v_mov_b32_e32 v67, v44
	v_mov_b32_e32 v70, v48
	v_mov_b32_e32 v71, v56
	v_mov_b32_e32 v40, v27
	v_mov_b32_e32 v42, v29
	v_mov_b32_e32 v44, v37
	v_mov_b32_e32 v46, v39
	v_mov_b32_e32 v56, v49
	v_mov_b32_e32 v58, v51
	v_mov_b32_e32 v62, v53
	v_mov_b32_e32 v64, v55
	s_waitcnt vmcnt(0)
	v_div_scale_f32 v15, s[46:47], v13, v13, s90
	v_rcp_f32_e32 v19, v15
	v_div_scale_f32 v17, vcc, s90, v13, s90
	v_fma_f32 v21, -v15, v19, 1.0
	v_fmac_f32_e32 v19, v21, v19
	v_mul_f32_e32 v21, v17, v19
	v_fma_f32 v26, -v15, v21, v17
	v_fmac_f32_e32 v21, v26, v19
	v_fma_f32 v15, -v15, v21, v17
	v_div_fmas_f32 v15, v15, v19, v21
	v_div_fixup_f32 v15, v15, v13, s90
	v_cmp_lt_f32_e32 vcc, 0, v13
	s_nop 1
	v_cndmask_b32_e32 v26, 0, v15, vcc
	v_pk_fma_f32 v[24:25], v[24:25], v[26:27], s[78:79] op_sel_hi:[1,0,0]
	v_pk_fma_f32 v[68:69], v[68:69], v[26:27], s[78:79] op_sel_hi:[1,0,0]
	v_pk_fma_f32 v[72:73], v[72:73], v[26:27], s[78:79] op_sel_hi:[1,0,0]
	v_pk_fma_f32 v[74:75], v[74:75], v[26:27], s[78:79] op_sel_hi:[1,0,0]
	v_pk_fma_f32 v[76:77], v[76:77], v[26:27], s[78:79] op_sel_hi:[1,0,0]
	v_pk_fma_f32 v[22:23], v[22:23], v[26:27], s[78:79] op_sel_hi:[1,0,0]
	v_pk_fma_f32 v[66:67], v[66:67], v[26:27], s[78:79] op_sel_hi:[1,0,0]
	v_pk_fma_f32 v[70:71], v[70:71], v[26:27], s[78:79] op_sel_hi:[1,0,0]
	v_lshlrev_b32_e32 v13, 8, v25
	v_lshlrev_b32_e32 v15, 8, v24
	v_lshlrev_b32_e32 v21, 24, v69
	v_lshlrev_b32_e32 v24, 24, v68
	v_lshlrev_b32_e32 v25, 8, v73
	v_lshlrev_b32_e32 v26, 8, v72
	v_lshlrev_b32_e32 v28, 16, v75
	v_lshlrev_b32_e32 v35, 16, v74
	v_lshlrev_b32_e32 v36, 24, v77
	v_lshlrev_b32_e32 v38, 24, v76
	v_lshlrev_b32_e32 v17, 16, v67
	v_lshlrev_b32_e32 v19, 16, v66
	v_and_b32_e32 v13, 0xff00, v13
	v_and_b32_e32 v15, 0xff00, v15
	v_or_b32_sdwa v21, v21, v23 dst_sel:DWORD dst_unused:UNUSED_PAD src0_sel:DWORD src1_sel:BYTE_0
	v_or_b32_sdwa v22, v24, v22 dst_sel:DWORD dst_unused:UNUSED_PAD src0_sel:DWORD src1_sel:BYTE_0
	v_and_b32_e32 v23, 0xff00, v25
	v_and_b32_e32 v24, 0xff00, v26
	v_and_b32_e32 v25, 0xff0000, v28
	v_and_b32_e32 v26, 0xff0000, v35
	v_or_b32_sdwa v28, v36, v71 dst_sel:DWORD dst_unused:UNUSED_PAD src0_sel:DWORD src1_sel:BYTE_0
	v_or_b32_sdwa v35, v38, v70 dst_sel:DWORD dst_unused:UNUSED_PAD src0_sel:DWORD src1_sel:BYTE_0
	v_and_b32_e32 v17, 0xff0000, v17
	v_and_b32_e32 v19, 0xff0000, v19
	v_or_b32_e32 v13, v21, v13
	v_or_b32_e32 v15, v22, v15
	v_or_b32_e32 v21, v28, v23
	v_or_b32_e32 v24, v35, v24
	v_or_b32_e32 v23, v13, v17
	v_or_b32_e32 v22, v15, v19
	v_or_b32_e32 v25, v21, v25
	v_or_b32_e32 v24, v24, v26
	global_store_dwordx4 v[60:61], v[22:25], off
	v_mov_b32_e32 v4, v201
	s_nop 0
	v_lshl_add_u64 v[22:23], v[2:3], 0, v[146:147]
	s_nop 0
	v_div_scale_f32 v2, s[46:47], v4, v4, s90
	v_rcp_f32_e32 v5, v2
	v_div_scale_f32 v3, vcc, s90, v4, s90
	v_fma_f32 v13, -v2, v5, 1.0
	v_fmac_f32_e32 v5, v13, v5
	v_mul_f32_e32 v13, v3, v5
	v_fma_f32 v15, -v2, v13, v3
	v_fmac_f32_e32 v13, v15, v5
	v_fma_f32 v2, -v2, v13, v3
	v_div_fmas_f32 v2, v2, v5, v13
	v_div_fixup_f32 v2, v2, v4, s90
	v_cmp_lt_f32_e32 vcc, 0, v4
	s_nop 1
	v_cndmask_b32_e32 v2, 0, v2, vcc
	v_pk_fma_f32 v[4:5], v[40:41], v[2:3], s[78:79] op_sel_hi:[1,0,0]
	v_pk_fma_f32 v[24:25], v[42:43], v[2:3], s[78:79] op_sel_hi:[1,0,0]
	v_pk_fma_f32 v[26:27], v[44:45], v[2:3], s[78:79] op_sel_hi:[1,0,0]
	v_pk_fma_f32 v[28:29], v[46:47], v[2:3], s[78:79] op_sel_hi:[1,0,0]
	v_pk_fma_f32 v[36:37], v[56:57], v[2:3], s[78:79] op_sel_hi:[1,0,0]
	v_pk_fma_f32 v[38:39], v[58:59], v[2:3], s[78:79] op_sel_hi:[1,0,0]
	v_pk_fma_f32 v[40:41], v[62:63], v[2:3], s[78:79] op_sel_hi:[1,0,0]
	v_pk_fma_f32 v[2:3], v[64:65], v[2:3], s[78:79] op_sel_hi:[1,0,0]
	v_lshlrev_b32_e32 v13, 8, v25
	v_lshlrev_b32_e32 v15, 8, v24
	v_lshlrev_b32_e32 v19, 16, v26
	v_lshlrev_b32_e32 v21, 24, v29
	v_lshlrev_b32_e32 v24, 24, v28
	v_lshlrev_b32_e32 v25, 8, v39
	v_lshlrev_b32_e32 v26, 8, v38
	v_lshlrev_b32_e32 v3, 24, v3
	v_lshlrev_b32_e32 v2, 24, v2
	v_lshlrev_b32_e32 v17, 16, v27
	v_lshlrev_b32_e32 v27, 16, v41
	v_lshlrev_b32_e32 v28, 16, v40
	v_and_b32_e32 v13, 0xff00, v13
	v_and_b32_e32 v15, 0xff00, v15
	v_or_b32_sdwa v5, v21, v5 dst_sel:DWORD dst_unused:UNUSED_PAD src0_sel:DWORD src1_sel:BYTE_0
	v_or_b32_sdwa v4, v24, v4 dst_sel:DWORD dst_unused:UNUSED_PAD src0_sel:DWORD src1_sel:BYTE_0
	v_and_b32_e32 v21, 0xff00, v25
	v_and_b32_e32 v24, 0xff00, v26
	v_or_b32_sdwa v3, v3, v37 dst_sel:DWORD dst_unused:UNUSED_PAD src0_sel:DWORD src1_sel:BYTE_0
	v_or_b32_sdwa v2, v2, v36 dst_sel:DWORD dst_unused:UNUSED_PAD src0_sel:DWORD src1_sel:BYTE_0
	v_and_b32_e32 v17, 0xff0000, v17
	v_and_b32_e32 v19, 0xff0000, v19
	v_and_b32_e32 v25, 0xff0000, v27
	v_and_b32_e32 v26, 0xff0000, v28
	v_or_b32_e32 v5, v5, v13
	v_or_b32_e32 v4, v4, v15
	v_or_b32_e32 v13, v3, v21
	v_or_b32_e32 v15, v2, v24
	v_or_b32_e32 v3, v5, v17
	v_or_b32_e32 v2, v4, v19
	v_or_b32_e32 v5, v13, v25
	v_or_b32_e32 v4, v15, v26
	global_store_dwordx4 v[22:23], v[2:5], off
	s_waitcnt lgkmcnt(0)
	s_cbranch_scc1 .LBB0_65
	s_branch .LBB0_7
